# class C (GEMM1 first, weight conversion afterwards) widened to 3 of every 4 workgroups
# speedup vs baseline: 1.0023x; 1.0023x over previous
_Z3fwd4Args:
	v_writelane_b32 v249, s0, 0
	v_writelane_b32 v249, s1, 1
	v_writelane_b32 v249, s2, 2
	v_mov_b32_e32 v250, v0
	s_and_b32 s101, s2, 3
	s_cmp_lg_u32 s101, 0
	s_cselect_b32 s101, 0x100, 0
